# attention unit epilogues de-serialised (16 gate loads up front, counted waits), MLA parked-Q loads batched
# baseline (speedup 1.0000x reference)
.LBB0_517:
	v_lshlrev_b64 v[4:5], 12, v[176:177]
	v_lshl_add_u64 v[2:3], v[172:173], 0, v[4:5]
	global_load_dwordx2 v[80:81], v[2:3], off
	global_load_dwordx2 v[82:83], v[2:3], off offset:16
	global_load_dwordx2 v[84:85], v[2:3], off offset:32
	global_load_dwordx2 v[86:87], v[2:3], off offset:48
	global_load_dwordx2 v[88:89], v[2:3], off offset:64
	global_load_dwordx2 v[90:91], v[2:3], off offset:80
	global_load_dwordx2 v[92:93], v[2:3], off offset:96
	global_load_dwordx2 v[94:95], v[2:3], off offset:112
	global_load_dwordx2 v[96:97], v[2:3], off offset:128
	global_load_dwordx2 v[98:99], v[2:3], off offset:144
	global_load_dwordx2 v[100:101], v[2:3], off offset:160
	global_load_dwordx2 v[102:103], v[2:3], off offset:176
	global_load_dwordx2 v[104:105], v[2:3], off offset:192
	global_load_dwordx2 v[106:107], v[2:3], off offset:208
	global_load_dwordx2 v[108:109], v[2:3], off offset:224
	global_load_dwordx2 v[110:111], v[2:3], off offset:240
	v_rcp_f32_e32 v0, v163
	v_lshl_add_u64 v[4:5], v[170:171], 0, v[4:5]
	s_mov_b64 s[78:79], 0
	s_and_b64 vcc, exec, s[4:5]
	v_mul_f32_e32 v64, v0, v64
	v_mul_f32_e32 v65, v0, v65
	v_mul_f32_e32 v66, v0, v66
	v_mul_f32_e32 v67, v0, v67
	v_mul_f32_e32 v68, v0, v68
	v_mul_f32_e32 v69, v0, v69
	v_mul_f32_e32 v70, v0, v70
	v_mul_f32_e32 v71, v0, v71
	v_mul_f32_e32 v72, v0, v72
	v_mul_f32_e32 v73, v0, v73
	v_mul_f32_e32 v74, v0, v74
	v_mul_f32_e32 v75, v0, v75
	v_mul_f32_e32 v76, v0, v76
	v_mul_f32_e32 v77, v0, v77
	v_mul_f32_e32 v78, v0, v78
	v_mul_f32_e32 v79, v0, v79
	v_mul_f32_e32 v48, v0, v48
	v_mul_f32_e32 v49, v0, v49
	v_mul_f32_e32 v50, v0, v50
	v_mul_f32_e32 v51, v0, v51
	v_mul_f32_e32 v52, v0, v52
	v_mul_f32_e32 v53, v0, v53
	v_mul_f32_e32 v54, v0, v54
	v_mul_f32_e32 v55, v0, v55
	v_mul_f32_e32 v56, v0, v56
	v_mul_f32_e32 v57, v0, v57
	v_mul_f32_e32 v58, v0, v58
	v_mul_f32_e32 v59, v0, v59
	v_mul_f32_e32 v60, v0, v60
	v_mul_f32_e32 v61, v0, v61
	v_mul_f32_e32 v62, v0, v62
	v_mul_f32_e32 v63, v0, v63
	v_mul_f32_e32 v32, v0, v32
	v_mul_f32_e32 v33, v0, v33
	v_mul_f32_e32 v34, v0, v34
	v_mul_f32_e32 v35, v0, v35
	v_mul_f32_e32 v36, v0, v36
	v_mul_f32_e32 v37, v0, v37
	v_mul_f32_e32 v38, v0, v38
	v_mul_f32_e32 v39, v0, v39
	v_mul_f32_e32 v40, v0, v40
	v_mul_f32_e32 v41, v0, v41
	v_mul_f32_e32 v42, v0, v42
	v_mul_f32_e32 v43, v0, v43
	v_mul_f32_e32 v44, v0, v44
	v_mul_f32_e32 v45, v0, v45
	v_mul_f32_e32 v46, v0, v46
	v_mul_f32_e32 v47, v0, v47
	v_mul_f32_e32 v16, v0, v16
	v_mul_f32_e32 v17, v0, v17
	v_mul_f32_e32 v18, v0, v18
	v_mul_f32_e32 v19, v0, v19
	v_mul_f32_e32 v20, v0, v20
	v_mul_f32_e32 v21, v0, v21
	v_mul_f32_e32 v22, v0, v22
	v_mul_f32_e32 v23, v0, v23
	v_mul_f32_e32 v24, v0, v24
	v_mul_f32_e32 v25, v0, v25
	v_mul_f32_e32 v26, v0, v26
	v_mul_f32_e32 v27, v0, v27
	v_mul_f32_e32 v28, v0, v28
	v_mul_f32_e32 v29, v0, v29
	v_mul_f32_e32 v30, v0, v30
	v_mul_f32_e32 v31, v0, v31
	s_waitcnt vmcnt(14)
	v_lshlrev_b32_e32 v6, 16, v80
	v_and_b32_e32 v7, 0xffff0000, v80
	v_lshlrev_b32_e32 v8, 16, v81
	v_and_b32_e32 v9, 0xffff0000, v81
	v_lshlrev_b32_e32 v10, 16, v82
	v_and_b32_e32 v11, 0xffff0000, v82
	v_lshlrev_b32_e32 v12, 16, v83
	v_and_b32_e32 v13, 0xffff0000, v83
	v_mul_f32_e32 v6, v64, v6
	v_mul_f32_e32 v7, v65, v7
	v_mul_f32_e32 v8, v66, v8
	v_mul_f32_e32 v9, v67, v9
	v_mul_f32_e32 v10, v68, v10
	v_mul_f32_e32 v11, v69, v11
	v_mul_f32_e32 v12, v70, v12
	v_mul_f32_e32 v13, v71, v13
	v_cvt_pk_bf16_f32 v112, v6, v7
	v_cvt_pk_bf16_f32 v113, v8, v9
	v_cvt_pk_bf16_f32 v114, v10, v11
	v_cvt_pk_bf16_f32 v115, v12, v13
	s_nop 1
	v_permlane32_swap_b32_e32 v112, v114
	v_permlane32_swap_b32_e32 v113, v115
	global_store_dwordx4 v[4:5], v[112:115], off
	s_waitcnt vmcnt(13)
	v_lshlrev_b32_e32 v6, 16, v84
	v_and_b32_e32 v7, 0xffff0000, v84
	v_lshlrev_b32_e32 v8, 16, v85
	v_and_b32_e32 v9, 0xffff0000, v85
	v_lshlrev_b32_e32 v10, 16, v86
	v_and_b32_e32 v11, 0xffff0000, v86
	v_lshlrev_b32_e32 v12, 16, v87
	v_and_b32_e32 v13, 0xffff0000, v87
	v_mul_f32_e32 v6, v72, v6
	v_mul_f32_e32 v7, v73, v7
	v_mul_f32_e32 v8, v74, v8
	v_mul_f32_e32 v9, v75, v9
	v_mul_f32_e32 v10, v76, v10
	v_mul_f32_e32 v11, v77, v11
	v_mul_f32_e32 v12, v78, v12
	v_mul_f32_e32 v13, v79, v13
	v_cvt_pk_bf16_f32 v116, v6, v7
	v_cvt_pk_bf16_f32 v117, v8, v9
	v_cvt_pk_bf16_f32 v118, v10, v11
	v_cvt_pk_bf16_f32 v119, v12, v13
	s_nop 1
	v_permlane32_swap_b32_e32 v116, v118
	v_permlane32_swap_b32_e32 v117, v119
	global_store_dwordx4 v[4:5], v[116:119], off offset:32
	s_waitcnt vmcnt(12)
	v_lshlrev_b32_e32 v6, 16, v88
	v_and_b32_e32 v7, 0xffff0000, v88
	v_lshlrev_b32_e32 v8, 16, v89
	v_and_b32_e32 v9, 0xffff0000, v89
	v_lshlrev_b32_e32 v10, 16, v90
	v_and_b32_e32 v11, 0xffff0000, v90
	v_lshlrev_b32_e32 v12, 16, v91
	v_and_b32_e32 v13, 0xffff0000, v91
	v_mul_f32_e32 v6, v48, v6
	v_mul_f32_e32 v7, v49, v7
	v_mul_f32_e32 v8, v50, v8
	v_mul_f32_e32 v9, v51, v9
	v_mul_f32_e32 v10, v52, v10
	v_mul_f32_e32 v11, v53, v11
	v_mul_f32_e32 v12, v54, v12
	v_mul_f32_e32 v13, v55, v13
	v_cvt_pk_bf16_f32 v120, v6, v7
	v_cvt_pk_bf16_f32 v121, v8, v9
	v_cvt_pk_bf16_f32 v122, v10, v11
	v_cvt_pk_bf16_f32 v123, v12, v13
	s_nop 1
	v_permlane32_swap_b32_e32 v120, v122
	v_permlane32_swap_b32_e32 v121, v123
	global_store_dwordx4 v[4:5], v[120:123], off offset:64
	s_waitcnt vmcnt(11)
	v_lshlrev_b32_e32 v6, 16, v92
	v_and_b32_e32 v7, 0xffff0000, v92
	v_lshlrev_b32_e32 v8, 16, v93
	v_and_b32_e32 v9, 0xffff0000, v93
	v_lshlrev_b32_e32 v10, 16, v94
	v_and_b32_e32 v11, 0xffff0000, v94
	v_lshlrev_b32_e32 v12, 16, v95
	v_and_b32_e32 v13, 0xffff0000, v95
	v_mul_f32_e32 v6, v56, v6
	v_mul_f32_e32 v7, v57, v7
	v_mul_f32_e32 v8, v58, v8
	v_mul_f32_e32 v9, v59, v9
	v_mul_f32_e32 v10, v60, v10
	v_mul_f32_e32 v11, v61, v11
	v_mul_f32_e32 v12, v62, v12
	v_mul_f32_e32 v13, v63, v13
	v_cvt_pk_bf16_f32 v124, v6, v7
	v_cvt_pk_bf16_f32 v125, v8, v9
	v_cvt_pk_bf16_f32 v126, v10, v11
	v_cvt_pk_bf16_f32 v127, v12, v13
	s_nop 1
	v_permlane32_swap_b32_e32 v124, v126
	v_permlane32_swap_b32_e32 v125, v127
	global_store_dwordx4 v[4:5], v[124:127], off offset:96
	s_waitcnt vmcnt(10)
	v_lshlrev_b32_e32 v6, 16, v96
	v_and_b32_e32 v7, 0xffff0000, v96
	v_lshlrev_b32_e32 v8, 16, v97
	v_and_b32_e32 v9, 0xffff0000, v97
	v_lshlrev_b32_e32 v10, 16, v98
	v_and_b32_e32 v11, 0xffff0000, v98
	v_lshlrev_b32_e32 v12, 16, v99
	v_and_b32_e32 v13, 0xffff0000, v99
	v_mul_f32_e32 v6, v32, v6
	v_mul_f32_e32 v7, v33, v7
	v_mul_f32_e32 v8, v34, v8
	v_mul_f32_e32 v9, v35, v9
	v_mul_f32_e32 v10, v36, v10
	v_mul_f32_e32 v11, v37, v11
	v_mul_f32_e32 v12, v38, v12
	v_mul_f32_e32 v13, v39, v13
	v_cvt_pk_bf16_f32 v128, v6, v7
	v_cvt_pk_bf16_f32 v129, v8, v9
	v_cvt_pk_bf16_f32 v130, v10, v11
	v_cvt_pk_bf16_f32 v131, v12, v13
	s_nop 1
	v_permlane32_swap_b32_e32 v128, v130
	v_permlane32_swap_b32_e32 v129, v131
	global_store_dwordx4 v[4:5], v[128:131], off offset:128
	s_waitcnt vmcnt(9)
	v_lshlrev_b32_e32 v6, 16, v100
	v_and_b32_e32 v7, 0xffff0000, v100
	v_lshlrev_b32_e32 v8, 16, v101
	v_and_b32_e32 v9, 0xffff0000, v101
	v_lshlrev_b32_e32 v10, 16, v102
	v_and_b32_e32 v11, 0xffff0000, v102
	v_lshlrev_b32_e32 v12, 16, v103
	v_and_b32_e32 v13, 0xffff0000, v103
	v_mul_f32_e32 v6, v40, v6
	v_mul_f32_e32 v7, v41, v7
	v_mul_f32_e32 v8, v42, v8
	v_mul_f32_e32 v9, v43, v9
	v_mul_f32_e32 v10, v44, v10
	v_mul_f32_e32 v11, v45, v11
	v_mul_f32_e32 v12, v46, v12
	v_mul_f32_e32 v13, v47, v13
	v_cvt_pk_bf16_f32 v132, v6, v7
	v_cvt_pk_bf16_f32 v133, v8, v9
	v_cvt_pk_bf16_f32 v134, v10, v11
	v_cvt_pk_bf16_f32 v135, v12, v13
	s_nop 1
	v_permlane32_swap_b32_e32 v132, v134
	v_permlane32_swap_b32_e32 v133, v135
	global_store_dwordx4 v[4:5], v[132:135], off offset:160
	s_waitcnt vmcnt(8)
	v_lshlrev_b32_e32 v6, 16, v104
	v_and_b32_e32 v7, 0xffff0000, v104
	v_lshlrev_b32_e32 v8, 16, v105
	v_and_b32_e32 v9, 0xffff0000, v105
	v_lshlrev_b32_e32 v10, 16, v106
	v_and_b32_e32 v11, 0xffff0000, v106
	v_lshlrev_b32_e32 v12, 16, v107
	v_and_b32_e32 v13, 0xffff0000, v107
	v_mul_f32_e32 v6, v16, v6
	v_mul_f32_e32 v7, v17, v7
	v_mul_f32_e32 v8, v18, v8
	v_mul_f32_e32 v9, v19, v9
	v_mul_f32_e32 v10, v20, v10
	v_mul_f32_e32 v11, v21, v11
	v_mul_f32_e32 v12, v22, v12
	v_mul_f32_e32 v13, v23, v13
	v_cvt_pk_bf16_f32 v136, v6, v7
	v_cvt_pk_bf16_f32 v137, v8, v9
	v_cvt_pk_bf16_f32 v138, v10, v11
	v_cvt_pk_bf16_f32 v139, v12, v13
	s_nop 1
	v_permlane32_swap_b32_e32 v136, v138
	v_permlane32_swap_b32_e32 v137, v139
	global_store_dwordx4 v[4:5], v[136:139], off offset:192
	s_waitcnt vmcnt(7)
	v_lshlrev_b32_e32 v6, 16, v108
	v_and_b32_e32 v7, 0xffff0000, v108
	v_lshlrev_b32_e32 v8, 16, v109
	v_and_b32_e32 v9, 0xffff0000, v109
	v_lshlrev_b32_e32 v10, 16, v110
	v_and_b32_e32 v11, 0xffff0000, v110
	v_lshlrev_b32_e32 v12, 16, v111
	v_and_b32_e32 v13, 0xffff0000, v111
	v_mul_f32_e32 v6, v24, v6
	v_mul_f32_e32 v7, v25, v7
	v_mul_f32_e32 v8, v26, v8
	v_mul_f32_e32 v9, v27, v9
	v_mul_f32_e32 v10, v28, v10
	v_mul_f32_e32 v11, v29, v11
	v_mul_f32_e32 v12, v30, v12
	v_mul_f32_e32 v13, v31, v13
	v_cvt_pk_bf16_f32 v140, v6, v7
	v_cvt_pk_bf16_f32 v141, v8, v9
	v_cvt_pk_bf16_f32 v142, v10, v11
	v_cvt_pk_bf16_f32 v143, v12, v13
	s_nop 1
	v_permlane32_swap_b32_e32 v140, v142
	v_permlane32_swap_b32_e32 v141, v143
	global_store_dwordx4 v[4:5], v[140:143], off offset:224
	s_waitcnt lgkmcnt(0)
	s_barrier
	s_cbranch_vccnz .LBB0_559

.LBB0_520:
	s_lshl_b32 s9, s1, 8
	s_lshl_b32 s0, s2, 5
	s_add_i32 s8, s0, s9
	v_or_b32_e32 v176, s8, v184
	s_movk_i32 s6, 0xc00
	v_mad_i64_i32 v[12:13], s[6:7], v176, s6, v[174:175]
	global_load_dwordx4 v[112:115], v[12:13], off
	global_load_dwordx4 v[116:119], v[12:13], off offset:32
	global_load_dwordx4 v[120:123], v[12:13], off offset:64
	global_load_dwordx4 v[124:127], v[12:13], off offset:96
	global_load_dwordx4 v[128:131], v[12:13], off offset:128
	global_load_dwordx4 v[132:135], v[12:13], off offset:160
	global_load_dwordx4 v[136:139], v[12:13], off offset:192
	global_load_dwordx4 v[140:143], v[12:13], off offset:224
	global_load_dwordx4 v[8:11], v[12:13], off offset:256
	global_load_dwordx4 v[16:19], v[12:13], off offset:288
	global_load_dwordx4 v[20:23], v[12:13], off offset:320
	global_load_dwordx4 v[24:27], v[12:13], off offset:352
	v_lshl_add_u32 v169, s2, 12, v186
	s_mov_b64 s[6:7], -1
	s_and_b64 vcc, exec, s[4:5]
	s_waitcnt vmcnt(0)
	ds_write_b128 v169, v[8:11]
	ds_write_b128 v169, v[16:19] offset:1024
	ds_write_b128 v169, v[20:23] offset:2048
	ds_write_b128 v169, v[24:27] offset:3072
	s_cbranch_vccz .LBB0_552
	s_waitcnt vmcnt(0) lgkmcnt(0)
	s_barrier
	s_lshl_b32 s10, s2, 1
	s_and_b32 s6, s10, 4
	s_cbranch_execz .LBB0_553

.LBB0_560:
	v_lshlrev_b64 v[4:5], 1, v[150:151]
	v_lshl_add_u64 v[2:3], v[172:173], 0, v[4:5]
	global_load_dwordx2 v[80:81], v[2:3], off offset:2048
	global_load_dwordx2 v[82:83], v[2:3], off offset:2064
	global_load_dwordx2 v[84:85], v[2:3], off offset:2080
	global_load_dwordx2 v[86:87], v[2:3], off offset:2096
	global_load_dwordx2 v[88:89], v[2:3], off offset:2112
	global_load_dwordx2 v[90:91], v[2:3], off offset:2128
	global_load_dwordx2 v[92:93], v[2:3], off offset:2144
	global_load_dwordx2 v[94:95], v[2:3], off offset:2160
	global_load_dwordx2 v[96:97], v[2:3], off offset:2176
	global_load_dwordx2 v[98:99], v[2:3], off offset:2192
	global_load_dwordx2 v[100:101], v[2:3], off offset:2208
	global_load_dwordx2 v[102:103], v[2:3], off offset:2224
	global_load_dwordx2 v[104:105], v[2:3], off offset:2240
	global_load_dwordx2 v[106:107], v[2:3], off offset:2256
	global_load_dwordx2 v[108:109], v[2:3], off offset:2272
	global_load_dwordx2 v[110:111], v[2:3], off offset:2288
	v_rcp_f32_e32 v0, v154
	v_lshl_add_u64 v[4:5], v[170:171], 0, v[4:5]
	s_mov_b64 s[84:85], 0
	s_and_b64 vcc, exec, s[4:5]
	v_mul_f32_e32 v64, v0, v64
	v_mul_f32_e32 v65, v0, v65
	v_mul_f32_e32 v66, v0, v66
	v_mul_f32_e32 v67, v0, v67
	v_mul_f32_e32 v68, v0, v68
	v_mul_f32_e32 v69, v0, v69
	v_mul_f32_e32 v70, v0, v70
	v_mul_f32_e32 v71, v0, v71
	v_mul_f32_e32 v72, v0, v72
	v_mul_f32_e32 v73, v0, v73
	v_mul_f32_e32 v74, v0, v74
	v_mul_f32_e32 v75, v0, v75
	v_mul_f32_e32 v76, v0, v76
	v_mul_f32_e32 v77, v0, v77
	v_mul_f32_e32 v78, v0, v78
	v_mul_f32_e32 v79, v0, v79
	v_mul_f32_e32 v48, v0, v48
	v_mul_f32_e32 v49, v0, v49
	v_mul_f32_e32 v50, v0, v50
	v_mul_f32_e32 v51, v0, v51
	v_mul_f32_e32 v52, v0, v52
	v_mul_f32_e32 v53, v0, v53
	v_mul_f32_e32 v54, v0, v54
	v_mul_f32_e32 v55, v0, v55
	v_mul_f32_e32 v56, v0, v56
	v_mul_f32_e32 v57, v0, v57
	v_mul_f32_e32 v58, v0, v58
	v_mul_f32_e32 v59, v0, v59
	v_mul_f32_e32 v60, v0, v60
	v_mul_f32_e32 v61, v0, v61
	v_mul_f32_e32 v62, v0, v62
	v_mul_f32_e32 v63, v0, v63
	v_mul_f32_e32 v32, v0, v32
	v_mul_f32_e32 v33, v0, v33
	v_mul_f32_e32 v34, v0, v34
	v_mul_f32_e32 v35, v0, v35
	v_mul_f32_e32 v36, v0, v36
	v_mul_f32_e32 v37, v0, v37
	v_mul_f32_e32 v38, v0, v38
	v_mul_f32_e32 v39, v0, v39
	v_mul_f32_e32 v40, v0, v40
	v_mul_f32_e32 v41, v0, v41
	v_mul_f32_e32 v42, v0, v42
	v_mul_f32_e32 v43, v0, v43
	v_mul_f32_e32 v44, v0, v44
	v_mul_f32_e32 v45, v0, v45
	v_mul_f32_e32 v46, v0, v46
	v_mul_f32_e32 v47, v0, v47
	v_mul_f32_e32 v16, v0, v16
	v_mul_f32_e32 v17, v0, v17
	v_mul_f32_e32 v18, v0, v18
	v_mul_f32_e32 v19, v0, v19
	v_mul_f32_e32 v20, v0, v20
	v_mul_f32_e32 v21, v0, v21
	v_mul_f32_e32 v22, v0, v22
	v_mul_f32_e32 v23, v0, v23
	v_mul_f32_e32 v24, v0, v24
	v_mul_f32_e32 v25, v0, v25
	v_mul_f32_e32 v26, v0, v26
	v_mul_f32_e32 v27, v0, v27
	v_mul_f32_e32 v28, v0, v28
	v_mul_f32_e32 v29, v0, v29
	v_mul_f32_e32 v30, v0, v30
	v_mul_f32_e32 v31, v0, v31
	s_waitcnt vmcnt(14)
	v_lshlrev_b32_e32 v6, 16, v80
	v_and_b32_e32 v7, 0xffff0000, v80
	v_lshlrev_b32_e32 v8, 16, v81
	v_and_b32_e32 v9, 0xffff0000, v81
	v_lshlrev_b32_e32 v10, 16, v82
	v_and_b32_e32 v11, 0xffff0000, v82
	v_lshlrev_b32_e32 v12, 16, v83
	v_and_b32_e32 v13, 0xffff0000, v83
	v_mul_f32_e32 v6, v64, v6
	v_mul_f32_e32 v7, v65, v7
	v_mul_f32_e32 v8, v66, v8
	v_mul_f32_e32 v9, v67, v9
	v_mul_f32_e32 v10, v68, v10
	v_mul_f32_e32 v11, v69, v11
	v_mul_f32_e32 v12, v70, v12
	v_mul_f32_e32 v13, v71, v13
	v_cvt_pk_bf16_f32 v112, v6, v7
	v_cvt_pk_bf16_f32 v113, v8, v9
	v_cvt_pk_bf16_f32 v114, v10, v11
	v_cvt_pk_bf16_f32 v115, v12, v13
	s_nop 1
	v_permlane32_swap_b32_e32 v112, v114
	v_permlane32_swap_b32_e32 v113, v115
	global_store_dwordx4 v[4:5], v[112:115], off offset:2048
	s_waitcnt vmcnt(13)
	v_lshlrev_b32_e32 v6, 16, v84
	v_and_b32_e32 v7, 0xffff0000, v84
	v_lshlrev_b32_e32 v8, 16, v85
	v_and_b32_e32 v9, 0xffff0000, v85
	v_lshlrev_b32_e32 v10, 16, v86
	v_and_b32_e32 v11, 0xffff0000, v86
	v_lshlrev_b32_e32 v12, 16, v87
	v_and_b32_e32 v13, 0xffff0000, v87
	v_mul_f32_e32 v6, v72, v6
	v_mul_f32_e32 v7, v73, v7
	v_mul_f32_e32 v8, v74, v8
	v_mul_f32_e32 v9, v75, v9
	v_mul_f32_e32 v10, v76, v10
	v_mul_f32_e32 v11, v77, v11
	v_mul_f32_e32 v12, v78, v12
	v_mul_f32_e32 v13, v79, v13
	v_cvt_pk_bf16_f32 v116, v6, v7
	v_cvt_pk_bf16_f32 v117, v8, v9
	v_cvt_pk_bf16_f32 v118, v10, v11
	v_cvt_pk_bf16_f32 v119, v12, v13
	s_nop 1
	v_permlane32_swap_b32_e32 v116, v118
	v_permlane32_swap_b32_e32 v117, v119
	global_store_dwordx4 v[4:5], v[116:119], off offset:2080
	s_waitcnt vmcnt(12)
	v_lshlrev_b32_e32 v6, 16, v88
	v_and_b32_e32 v7, 0xffff0000, v88
	v_lshlrev_b32_e32 v8, 16, v89
	v_and_b32_e32 v9, 0xffff0000, v89
	v_lshlrev_b32_e32 v10, 16, v90
	v_and_b32_e32 v11, 0xffff0000, v90
	v_lshlrev_b32_e32 v12, 16, v91
	v_and_b32_e32 v13, 0xffff0000, v91
	v_mul_f32_e32 v6, v48, v6
	v_mul_f32_e32 v7, v49, v7
	v_mul_f32_e32 v8, v50, v8
	v_mul_f32_e32 v9, v51, v9
	v_mul_f32_e32 v10, v52, v10
	v_mul_f32_e32 v11, v53, v11
	v_mul_f32_e32 v12, v54, v12
	v_mul_f32_e32 v13, v55, v13
	v_cvt_pk_bf16_f32 v120, v6, v7
	v_cvt_pk_bf16_f32 v121, v8, v9
	v_cvt_pk_bf16_f32 v122, v10, v11
	v_cvt_pk_bf16_f32 v123, v12, v13
	s_nop 1
	v_permlane32_swap_b32_e32 v120, v122
	v_permlane32_swap_b32_e32 v121, v123
	global_store_dwordx4 v[4:5], v[120:123], off offset:2112
	s_waitcnt vmcnt(11)
	v_lshlrev_b32_e32 v6, 16, v92
	v_and_b32_e32 v7, 0xffff0000, v92
	v_lshlrev_b32_e32 v8, 16, v93
	v_and_b32_e32 v9, 0xffff0000, v93
	v_lshlrev_b32_e32 v10, 16, v94
	v_and_b32_e32 v11, 0xffff0000, v94
	v_lshlrev_b32_e32 v12, 16, v95
	v_and_b32_e32 v13, 0xffff0000, v95
	v_mul_f32_e32 v6, v56, v6
	v_mul_f32_e32 v7, v57, v7
	v_mul_f32_e32 v8, v58, v8
	v_mul_f32_e32 v9, v59, v9
	v_mul_f32_e32 v10, v60, v10
	v_mul_f32_e32 v11, v61, v11
	v_mul_f32_e32 v12, v62, v12
	v_mul_f32_e32 v13, v63, v13
	v_cvt_pk_bf16_f32 v124, v6, v7
	v_cvt_pk_bf16_f32 v125, v8, v9
	v_cvt_pk_bf16_f32 v126, v10, v11
	v_cvt_pk_bf16_f32 v127, v12, v13
	s_nop 1
	v_permlane32_swap_b32_e32 v124, v126
	v_permlane32_swap_b32_e32 v125, v127
	global_store_dwordx4 v[4:5], v[124:127], off offset:2144
	s_waitcnt vmcnt(10)
	v_lshlrev_b32_e32 v6, 16, v96
	v_and_b32_e32 v7, 0xffff0000, v96
	v_lshlrev_b32_e32 v8, 16, v97
	v_and_b32_e32 v9, 0xffff0000, v97
	v_lshlrev_b32_e32 v10, 16, v98
	v_and_b32_e32 v11, 0xffff0000, v98
	v_lshlrev_b32_e32 v12, 16, v99
	v_and_b32_e32 v13, 0xffff0000, v99
	v_mul_f32_e32 v6, v32, v6
	v_mul_f32_e32 v7, v33, v7
	v_mul_f32_e32 v8, v34, v8
	v_mul_f32_e32 v9, v35, v9
	v_mul_f32_e32 v10, v36, v10
	v_mul_f32_e32 v11, v37, v11
	v_mul_f32_e32 v12, v38, v12
	v_mul_f32_e32 v13, v39, v13
	v_cvt_pk_bf16_f32 v128, v6, v7
	v_cvt_pk_bf16_f32 v129, v8, v9
	v_cvt_pk_bf16_f32 v130, v10, v11
	v_cvt_pk_bf16_f32 v131, v12, v13
	s_nop 1
	v_permlane32_swap_b32_e32 v128, v130
	v_permlane32_swap_b32_e32 v129, v131
	global_store_dwordx4 v[4:5], v[128:131], off offset:2176
	s_waitcnt vmcnt(9)
	v_lshlrev_b32_e32 v6, 16, v100
	v_and_b32_e32 v7, 0xffff0000, v100
	v_lshlrev_b32_e32 v8, 16, v101
	v_and_b32_e32 v9, 0xffff0000, v101
	v_lshlrev_b32_e32 v10, 16, v102
	v_and_b32_e32 v11, 0xffff0000, v102
	v_lshlrev_b32_e32 v12, 16, v103
	v_and_b32_e32 v13, 0xffff0000, v103
	v_mul_f32_e32 v6, v40, v6
	v_mul_f32_e32 v7, v41, v7
	v_mul_f32_e32 v8, v42, v8
	v_mul_f32_e32 v9, v43, v9
	v_mul_f32_e32 v10, v44, v10
	v_mul_f32_e32 v11, v45, v11
	v_mul_f32_e32 v12, v46, v12
	v_mul_f32_e32 v13, v47, v13
	v_cvt_pk_bf16_f32 v132, v6, v7
	v_cvt_pk_bf16_f32 v133, v8, v9
	v_cvt_pk_bf16_f32 v134, v10, v11
	v_cvt_pk_bf16_f32 v135, v12, v13
	s_nop 1
	v_permlane32_swap_b32_e32 v132, v134
	v_permlane32_swap_b32_e32 v133, v135
	global_store_dwordx4 v[4:5], v[132:135], off offset:2208
	s_waitcnt vmcnt(8)
	v_lshlrev_b32_e32 v6, 16, v104
	v_and_b32_e32 v7, 0xffff0000, v104
	v_lshlrev_b32_e32 v8, 16, v105
	v_and_b32_e32 v9, 0xffff0000, v105
	v_lshlrev_b32_e32 v10, 16, v106
	v_and_b32_e32 v11, 0xffff0000, v106
	v_lshlrev_b32_e32 v12, 16, v107
	v_and_b32_e32 v13, 0xffff0000, v107
	v_mul_f32_e32 v6, v16, v6
	v_mul_f32_e32 v7, v17, v7
	v_mul_f32_e32 v8, v18, v8
	v_mul_f32_e32 v9, v19, v9
	v_mul_f32_e32 v10, v20, v10
	v_mul_f32_e32 v11, v21, v11
	v_mul_f32_e32 v12, v22, v12
	v_mul_f32_e32 v13, v23, v13
	v_cvt_pk_bf16_f32 v136, v6, v7
	v_cvt_pk_bf16_f32 v137, v8, v9
	v_cvt_pk_bf16_f32 v138, v10, v11
	v_cvt_pk_bf16_f32 v139, v12, v13
	s_nop 1
	v_permlane32_swap_b32_e32 v136, v138
	v_permlane32_swap_b32_e32 v137, v139
	global_store_dwordx4 v[4:5], v[136:139], off offset:2240
	s_waitcnt vmcnt(7)
	v_lshlrev_b32_e32 v6, 16, v108
	v_and_b32_e32 v7, 0xffff0000, v108
	v_lshlrev_b32_e32 v8, 16, v109
	v_and_b32_e32 v9, 0xffff0000, v109
	v_lshlrev_b32_e32 v10, 16, v110
	v_and_b32_e32 v11, 0xffff0000, v110
	v_lshlrev_b32_e32 v12, 16, v111
	v_and_b32_e32 v13, 0xffff0000, v111
	v_mul_f32_e32 v6, v24, v6
	v_mul_f32_e32 v7, v25, v7
	v_mul_f32_e32 v8, v26, v8
	v_mul_f32_e32 v9, v27, v9
	v_mul_f32_e32 v10, v28, v10
	v_mul_f32_e32 v11, v29, v11
	v_mul_f32_e32 v12, v30, v12
	v_mul_f32_e32 v13, v31, v13
	v_cvt_pk_bf16_f32 v140, v6, v7
	v_cvt_pk_bf16_f32 v141, v8, v9
	v_cvt_pk_bf16_f32 v142, v10, v11
	v_cvt_pk_bf16_f32 v143, v12, v13
	s_nop 1
	v_permlane32_swap_b32_e32 v140, v142
	v_permlane32_swap_b32_e32 v141, v143
	global_store_dwordx4 v[4:5], v[140:143], off offset:2272
	s_waitcnt lgkmcnt(0)
	s_barrier
	s_cbranch_vccnz .LBB0_515
